# v18
# speedup vs baseline: 1.0024x; 1.0024x over previous
; #define PG8_STAGE(bufoff, gbase, voff) do { _Pragma("unroll") for (int _i = 0; _i < 2; ++_i) \
;         __builtin_amdgcn_global_load_lds((const unsigned*)((const char*)(gbase) + (voff)[_i]), (LAS unsigned*)(lds + (bufoff) + ldsw + _i * 8192), 16, 0, 0); } while (0)
; #define PG8_LDA(dst, b, h) do { _Pragma("unroll") for (int m = 0; m < 4; ++m) _Pragma("unroll") for (int k = 0; k < 2; ++k) dst[m][k] = *(const LAS bf16x8*)(lds + PG8_SA(b, h) + aoff + m * 2048 + k * 1024); } while (0)
; #define PG8_LDB(dst, b, h) do { _Pragma("unroll") for (int n = 0; n < 2; ++n) _Pragma("unroll") for (int k = 0; k < 2; ++k) dst[n][k] = *(const LAS bf16x8*)(lds + PG8_SB(b, h) + boff + n * 2048 + k * 1024); } while (0)
; #define PG8_SCHED __builtin_amdgcn_sched_barrier(0)
; template <class Epi, class Sched>
; __device__ __forceinline__ void gemm_phase(LAS unsigned char* lds, const int tid, const int K, const int ldaB, const int ldbB, const Sched& S, const Epi& E) {
;     ...
;         const char* nA = has_next ? nxt.A : cA; const char* nB = has_next ? nxt.B : cB;
;         for (int t = 0; t < nt; t += 2) {
;             const bool last = (t == nt - 2);
;             const char* a1 = cA + (size_t)(t + 1) * kstep;
;             const char* a2 = last ? nA : cA + (size_t)(t + 2) * kstep; const char* b2 = last ? nB : cB + (size_t)(t + 2) * kstep;
;             const char* a3 = a2 + kstep; const char* b3 = b2 + kstep;
;             PG8_LDB(B0, 0, 0); PG8_LDB(B1, 0, 1); PG8_SCHED; PG8_LDA(At, 0, 0); PG8_STAGE(PG8_SA(1, 1), a1 + hstepA, voffA);
;     ...
;         for (int a = 0; a < 2; ++a)
; #pragma unroll
;             for (int b = 0; b < 2; ++b)
; #pragma unroll
;                 for (int m = 0; m < 4; ++m)
; #pragma unroll
;                     for (int n = 0; n < 2; ++n) acc[a][b][m][n] = (f32x4){0.f, 0.f, 0.f, 0.f};
.LBB0_39:
	s_add_u32 s40, s26, 0x100
	s_addc_u32 s41, s27, 0
	s_add_u32 s0, s12, 0x80080
	v_mov_b32_e32 v2, 0
	s_addc_u32 s1, s13, 0
	s_mov_b32 s85, -2
	v_mov_b32_e32 v3, v2
	v_mov_b32_e32 v4, v2
	v_mov_b32_e32 v5, v2
	v_mov_b32_e32 v46, v2
	v_mov_b32_e32 v47, v2
	v_mov_b32_e32 v48, v2
	v_mov_b32_e32 v49, v2
	v_mov_b32_e32 v102, v2
	v_mov_b32_e32 v103, v2
	v_mov_b32_e32 v104, v2
	v_mov_b32_e32 v105, v2
	v_mov_b32_e32 v142, v2
	v_mov_b32_e32 v143, v2
	v_mov_b32_e32 v144, v2
	v_mov_b32_e32 v145, v2
	v_mov_b32_e32 v150, v2
	v_mov_b32_e32 v151, v2
	v_mov_b32_e32 v152, v2
	v_mov_b32_e32 v153, v2
	v_mov_b32_e32 v114, v2
	v_mov_b32_e32 v115, v2
	v_mov_b32_e32 v116, v2
	v_mov_b32_e32 v117, v2
	v_mov_b32_e32 v54, v2
	v_mov_b32_e32 v55, v2
	v_mov_b32_e32 v56, v2
	v_mov_b32_e32 v57, v2
	v_mov_b32_e32 v14, v2
	v_mov_b32_e32 v15, v2
	v_mov_b32_e32 v16, v2
	v_mov_b32_e32 v17, v2
	v_mov_b32_e32 v6, v2
	v_mov_b32_e32 v7, v2
	v_mov_b32_e32 v8, v2
	v_mov_b32_e32 v9, v2
	v_mov_b32_e32 v10, v2
	v_mov_b32_e32 v11, v2
	v_mov_b32_e32 v12, v2
	v_mov_b32_e32 v13, v2
	v_mov_b32_e32 v26, v2
	v_mov_b32_e32 v27, v2
	v_mov_b32_e32 v28, v2
	v_mov_b32_e32 v29, v2
	v_mov_b32_e32 v34, v2
	v_mov_b32_e32 v35, v2
	v_mov_b32_e32 v36, v2
	v_mov_b32_e32 v37, v2
	v_mov_b32_e32 v42, v2
	v_mov_b32_e32 v43, v2
	v_mov_b32_e32 v44, v2
	v_mov_b32_e32 v45, v2
	v_mov_b32_e32 v50, v2
	v_mov_b32_e32 v51, v2
	v_mov_b32_e32 v52, v2
	v_mov_b32_e32 v53, v2
	v_mov_b32_e32 v58, v2
	v_mov_b32_e32 v59, v2
	v_mov_b32_e32 v60, v2
	v_mov_b32_e32 v61, v2
	v_mov_b32_e32 v62, v2
	v_mov_b32_e32 v63, v2
	v_mov_b32_e32 v64, v2
	v_mov_b32_e32 v65, v2
	v_mov_b32_e32 v18, v2
	v_mov_b32_e32 v19, v2
	v_mov_b32_e32 v20, v2
	v_mov_b32_e32 v21, v2
	v_mov_b32_e32 v22, v2
	v_mov_b32_e32 v23, v2
	v_mov_b32_e32 v24, v2
	v_mov_b32_e32 v25, v2
	v_mov_b32_e32 v30, v2
	v_mov_b32_e32 v31, v2
	v_mov_b32_e32 v32, v2
	v_mov_b32_e32 v33, v2
	v_mov_b32_e32 v38, v2
	v_mov_b32_e32 v39, v2
	v_mov_b32_e32 v40, v2
	v_mov_b32_e32 v41, v2
	v_mov_b32_e32 v94, v2
	v_mov_b32_e32 v95, v2
	v_mov_b32_e32 v96, v2
	v_mov_b32_e32 v97, v2
	v_mov_b32_e32 v110, v2
	v_mov_b32_e32 v111, v2
	v_mov_b32_e32 v112, v2
	v_mov_b32_e32 v113, v2
	v_mov_b32_e32 v122, v2
	v_mov_b32_e32 v123, v2
	v_mov_b32_e32 v124, v2
	v_mov_b32_e32 v125, v2
	v_mov_b32_e32 v130, v2
	v_mov_b32_e32 v131, v2
	v_mov_b32_e32 v132, v2
	v_mov_b32_e32 v133, v2
	v_mov_b32_e32 v138, v2
	v_mov_b32_e32 v139, v2
	v_mov_b32_e32 v140, v2
	v_mov_b32_e32 v141, v2
	v_mov_b32_e32 v146, v2
	v_mov_b32_e32 v147, v2
	v_mov_b32_e32 v148, v2
	v_mov_b32_e32 v149, v2
	v_mov_b32_e32 v154, v2
	v_mov_b32_e32 v155, v2
	v_mov_b32_e32 v156, v2
	v_mov_b32_e32 v157, v2
	v_mov_b32_e32 v158, v2
	v_mov_b32_e32 v159, v2
	v_mov_b32_e32 v160, v2
	v_mov_b32_e32 v161, v2
	v_mov_b32_e32 v106, v2
	v_mov_b32_e32 v107, v2
	v_mov_b32_e32 v108, v2
	v_mov_b32_e32 v109, v2
	v_mov_b32_e32 v118, v2
	v_mov_b32_e32 v119, v2
	v_mov_b32_e32 v120, v2
	v_mov_b32_e32 v121, v2
	v_mov_b32_e32 v126, v2
	v_mov_b32_e32 v127, v2
	v_mov_b32_e32 v128, v2
	v_mov_b32_e32 v129, v2
	v_mov_b32_e32 v134, v2
	v_mov_b32_e32 v135, v2
	v_mov_b32_e32 v136, v2
	v_mov_b32_e32 v137, v2

; #define PG8_STAGE(bufoff, gbase, voff) do { _Pragma("unroll") for (int _i = 0; _i < 2; ++_i) \
;         __builtin_amdgcn_global_load_lds((const unsigned*)((const char*)(gbase) + (voff)[_i]), (LAS unsigned*)(lds + (bufoff) + ldsw + _i * 8192), 16, 0, 0); } while (0)
; #define PG8_LDA(dst, b, h) do { _Pragma("unroll") for (int m = 0; m < 4; ++m) _Pragma("unroll") for (int k = 0; k < 2; ++k) dst[m][k] = *(const LAS bf16x8*)(lds + PG8_SA(b, h) + aoff + m * 2048 + k * 1024); } while (0)
; #define PG8_LDB(dst, b, h) do { _Pragma("unroll") for (int n = 0; n < 2; ++n) _Pragma("unroll") for (int k = 0; k < 2; ++k) dst[n][k] = *(const LAS bf16x8*)(lds + PG8_SB(b, h) + boff + n * 2048 + k * 1024); } while (0)
; #define PG8_SCHED __builtin_amdgcn_sched_barrier(0)
; template <class Epi, class Sched>
; __device__ __forceinline__ void gemm_phase(LAS unsigned char* lds, const int tid, const int K, const int ldaB, const int ldbB, const Sched& S, const Epi& E) {
;     ...
;         const char* nA = has_next ? nxt.A : cA; const char* nB = has_next ? nxt.B : cB;
;         for (int t = 0; t < nt; t += 2) {
;             const bool last = (t == nt - 2);
;             const char* a1 = cA + (size_t)(t + 1) * kstep;
;             const char* a2 = last ? nA : cA + (size_t)(t + 2) * kstep; const char* b2 = last ? nB : cB + (size_t)(t + 2) * kstep;
;             const char* a3 = a2 + kstep; const char* b3 = b2 + kstep;
;             PG8_LDB(B0, 0, 0); PG8_LDB(B1, 0, 1); PG8_SCHED; PG8_LDA(At, 0, 0); PG8_STAGE(PG8_SA(1, 1), a1 + hstepA, voffA);
;     ...
;         for (int a = 0; a < 2; ++a)
; #pragma unroll
;             for (int b = 0; b < 2; ++b)
; #pragma unroll
;                 for (int m = 0; m < 4; ++m)
; #pragma unroll
;                     for (int n = 0; n < 2; ++n) acc[a][b][m][n] = (f32x4){0.f, 0.f, 0.f, 0.f};
.LBB0_106:
	s_add_u32 s74, s12, 0x100
	s_addc_u32 s75, s13, 0
	s_add_u32 s12, s22, 0x80080
	v_mov_b32_e32 v2, 0
	s_addc_u32 s13, s23, 0
	s_mov_b32 s76, -2
	v_mov_b32_e32 v3, v2
	v_mov_b32_e32 v4, v2
	v_mov_b32_e32 v5, v2
	v_mov_b32_e32 v6, v2
	v_mov_b32_e32 v7, v2
	v_mov_b32_e32 v8, v2
	v_mov_b32_e32 v9, v2
	v_mov_b32_e32 v18, v2
	v_mov_b32_e32 v19, v2
	v_mov_b32_e32 v20, v2
	v_mov_b32_e32 v21, v2
	v_mov_b32_e32 v22, v2
	v_mov_b32_e32 v23, v2
	v_mov_b32_e32 v24, v2
	v_mov_b32_e32 v25, v2
	v_mov_b32_e32 v34, v2
	v_mov_b32_e32 v35, v2
	v_mov_b32_e32 v36, v2
	v_mov_b32_e32 v37, v2
	v_mov_b32_e32 v38, v2
	v_mov_b32_e32 v39, v2
	v_mov_b32_e32 v40, v2
	v_mov_b32_e32 v41, v2
	v_mov_b32_e32 v50, v2
	v_mov_b32_e32 v51, v2
	v_mov_b32_e32 v52, v2
	v_mov_b32_e32 v53, v2
	v_mov_b32_e32 v54, v2
	v_mov_b32_e32 v55, v2
	v_mov_b32_e32 v56, v2
	v_mov_b32_e32 v57, v2
	v_mov_b32_e32 v10, v2
	v_mov_b32_e32 v11, v2
	v_mov_b32_e32 v12, v2
	v_mov_b32_e32 v13, v2
	v_mov_b32_e32 v14, v2
	v_mov_b32_e32 v15, v2
	v_mov_b32_e32 v16, v2
	v_mov_b32_e32 v17, v2
	v_mov_b32_e32 v26, v2
	v_mov_b32_e32 v27, v2
	v_mov_b32_e32 v28, v2
	v_mov_b32_e32 v29, v2
	v_mov_b32_e32 v30, v2
	v_mov_b32_e32 v31, v2
	v_mov_b32_e32 v32, v2
	v_mov_b32_e32 v33, v2
	v_mov_b32_e32 v42, v2
	v_mov_b32_e32 v43, v2
	v_mov_b32_e32 v44, v2
	v_mov_b32_e32 v45, v2
	v_mov_b32_e32 v46, v2
	v_mov_b32_e32 v47, v2
	v_mov_b32_e32 v48, v2
	v_mov_b32_e32 v49, v2
	v_mov_b32_e32 v58, v2
	v_mov_b32_e32 v59, v2
	v_mov_b32_e32 v60, v2
	v_mov_b32_e32 v61, v2
	v_mov_b32_e32 v62, v2
	v_mov_b32_e32 v63, v2
	v_mov_b32_e32 v64, v2
	v_mov_b32_e32 v65, v2
	v_mov_b32_e32 v66, v2
	v_mov_b32_e32 v67, v2
	v_mov_b32_e32 v68, v2
	v_mov_b32_e32 v69, v2
	v_mov_b32_e32 v70, v2
	v_mov_b32_e32 v71, v2
	v_mov_b32_e32 v72, v2
	v_mov_b32_e32 v73, v2
	v_mov_b32_e32 v98, v2
	v_mov_b32_e32 v99, v2
	v_mov_b32_e32 v100, v2
	v_mov_b32_e32 v101, v2
	v_mov_b32_e32 v102, v2
	v_mov_b32_e32 v103, v2
	v_mov_b32_e32 v104, v2
	v_mov_b32_e32 v105, v2
	v_mov_b32_e32 v114, v2
	v_mov_b32_e32 v115, v2
	v_mov_b32_e32 v116, v2
	v_mov_b32_e32 v117, v2
	v_mov_b32_e32 v118, v2
	v_mov_b32_e32 v119, v2
	v_mov_b32_e32 v120, v2
	v_mov_b32_e32 v121, v2
	v_mov_b32_e32 v130, v2
	v_mov_b32_e32 v131, v2
	v_mov_b32_e32 v132, v2
	v_mov_b32_e32 v133, v2
	v_mov_b32_e32 v134, v2
	v_mov_b32_e32 v135, v2
	v_mov_b32_e32 v136, v2
	v_mov_b32_e32 v137, v2
	v_mov_b32_e32 v74, v2
	v_mov_b32_e32 v75, v2
	v_mov_b32_e32 v76, v2
	v_mov_b32_e32 v77, v2
	v_mov_b32_e32 v78, v2
	v_mov_b32_e32 v79, v2
	v_mov_b32_e32 v80, v2
	v_mov_b32_e32 v81, v2
	v_mov_b32_e32 v106, v2
	v_mov_b32_e32 v107, v2
	v_mov_b32_e32 v108, v2
	v_mov_b32_e32 v109, v2
	v_mov_b32_e32 v110, v2
	v_mov_b32_e32 v111, v2
	v_mov_b32_e32 v112, v2
	v_mov_b32_e32 v113, v2
	v_mov_b32_e32 v122, v2
	v_mov_b32_e32 v123, v2
	v_mov_b32_e32 v124, v2
	v_mov_b32_e32 v125, v2
	v_mov_b32_e32 v126, v2
	v_mov_b32_e32 v127, v2
	v_mov_b32_e32 v128, v2
	v_mov_b32_e32 v129, v2
	v_mov_b32_e32 v138, v2
	v_mov_b32_e32 v139, v2
	v_mov_b32_e32 v140, v2
	v_mov_b32_e32 v141, v2
	v_mov_b32_e32 v142, v2
	v_mov_b32_e32 v143, v2
	v_mov_b32_e32 v144, v2
	v_mov_b32_e32 v145, v2

; #define PG8_STAGE(bufoff, gbase, voff) do { _Pragma("unroll") for (int _i = 0; _i < 2; ++_i) \
;         __builtin_amdgcn_global_load_lds((const unsigned*)((const char*)(gbase) + (voff)[_i]), (LAS unsigned*)(lds + (bufoff) + ldsw + _i * 8192), 16, 0, 0); } while (0)
; #define PG8_LDA(dst, b, h) do { _Pragma("unroll") for (int m = 0; m < 4; ++m) _Pragma("unroll") for (int k = 0; k < 2; ++k) dst[m][k] = *(const LAS bf16x8*)(lds + PG8_SA(b, h) + aoff + m * 2048 + k * 1024); } while (0)
; #define PG8_LDB(dst, b, h) do { _Pragma("unroll") for (int n = 0; n < 2; ++n) _Pragma("unroll") for (int k = 0; k < 2; ++k) dst[n][k] = *(const LAS bf16x8*)(lds + PG8_SB(b, h) + boff + n * 2048 + k * 1024); } while (0)
; #define PG8_SCHED __builtin_amdgcn_sched_barrier(0)
; template <class Epi, class Sched>
; __device__ __forceinline__ void gemm_phase(LAS unsigned char* lds, const int tid, const int K, const int ldaB, const int ldbB, const Sched& S, const Epi& E) {
;     ...
;         const char* nA = has_next ? nxt.A : cA; const char* nB = has_next ? nxt.B : cB;
;         for (int t = 0; t < nt; t += 2) {
;             const bool last = (t == nt - 2);
;             const char* a1 = cA + (size_t)(t + 1) * kstep;
;             const char* a2 = last ? nA : cA + (size_t)(t + 2) * kstep; const char* b2 = last ? nB : cB + (size_t)(t + 2) * kstep;
;             const char* a3 = a2 + kstep; const char* b3 = b2 + kstep;
;             PG8_LDB(B0, 0, 0); PG8_LDB(B1, 0, 1); PG8_SCHED; PG8_LDA(At, 0, 0); PG8_STAGE(PG8_SA(1, 1), a1 + hstepA, voffA);
;     ...
;         for (int a = 0; a < 2; ++a)
; #pragma unroll
;             for (int b = 0; b < 2; ++b)
; #pragma unroll
;                 for (int m = 0; m < 4; ++m)
; #pragma unroll
;                     for (int n = 0; n < 2; ++n) acc[a][b][m][n] = (f32x4){0.f, 0.f, 0.f, 0.f};
.LBB0_151:
	s_and_b64 s[30:31], s[24:25], exec
	s_cselect_b32 s75, s9, s27
	s_cselect_b32 s76, s8, s26
	s_cselect_b32 s77, s11, s29
	s_cselect_b32 s78, s10, s28
	s_add_u32 s79, s28, 0x100
	s_addc_u32 s82, s29, 0
	s_add_u32 s26, s26, 0x48080
	v_mov_b32_e32 v2, 0
	s_addc_u32 s27, s27, 0
	s_mov_b32 s83, -2
	v_mov_b32_e32 v3, v2
	v_mov_b32_e32 v4, v2
	v_mov_b32_e32 v5, v2
	v_mov_b32_e32 v6, v2
	v_mov_b32_e32 v7, v2
	v_mov_b32_e32 v8, v2
	v_mov_b32_e32 v9, v2
	v_mov_b32_e32 v10, v2
	v_mov_b32_e32 v11, v2
	v_mov_b32_e32 v12, v2
	v_mov_b32_e32 v13, v2
	v_mov_b32_e32 v14, v2
	v_mov_b32_e32 v15, v2
	v_mov_b32_e32 v16, v2
	v_mov_b32_e32 v17, v2
	v_mov_b32_e32 v26, v2
	v_mov_b32_e32 v27, v2
	v_mov_b32_e32 v28, v2
	v_mov_b32_e32 v29, v2
	v_mov_b32_e32 v30, v2
	v_mov_b32_e32 v31, v2
	v_mov_b32_e32 v32, v2
	v_mov_b32_e32 v33, v2
	v_mov_b32_e32 v42, v2
	v_mov_b32_e32 v43, v2
	v_mov_b32_e32 v44, v2
	v_mov_b32_e32 v45, v2
	v_mov_b32_e32 v46, v2
	v_mov_b32_e32 v47, v2
	v_mov_b32_e32 v48, v2
	v_mov_b32_e32 v49, v2
	v_mov_b32_e32 v18, v2
	v_mov_b32_e32 v19, v2
	v_mov_b32_e32 v20, v2
	v_mov_b32_e32 v21, v2
	v_mov_b32_e32 v22, v2
	v_mov_b32_e32 v23, v2
	v_mov_b32_e32 v24, v2
	v_mov_b32_e32 v25, v2
	v_mov_b32_e32 v34, v2
	v_mov_b32_e32 v35, v2
	v_mov_b32_e32 v36, v2
	v_mov_b32_e32 v37, v2
	v_mov_b32_e32 v38, v2
	v_mov_b32_e32 v39, v2
	v_mov_b32_e32 v40, v2
	v_mov_b32_e32 v41, v2
	v_mov_b32_e32 v50, v2
	v_mov_b32_e32 v51, v2
	v_mov_b32_e32 v52, v2
	v_mov_b32_e32 v53, v2
	v_mov_b32_e32 v54, v2
	v_mov_b32_e32 v55, v2
	v_mov_b32_e32 v56, v2
	v_mov_b32_e32 v57, v2
	v_mov_b32_e32 v58, v2
	v_mov_b32_e32 v59, v2
	v_mov_b32_e32 v60, v2
	v_mov_b32_e32 v61, v2
	v_mov_b32_e32 v62, v2
	v_mov_b32_e32 v63, v2
	v_mov_b32_e32 v64, v2
	v_mov_b32_e32 v65, v2
	v_mov_b32_e32 v66, v2
	v_mov_b32_e32 v67, v2
	v_mov_b32_e32 v68, v2
	v_mov_b32_e32 v69, v2
	v_mov_b32_e32 v70, v2
	v_mov_b32_e32 v71, v2
	v_mov_b32_e32 v72, v2
	v_mov_b32_e32 v73, v2
	v_mov_b32_e32 v74, v2
	v_mov_b32_e32 v75, v2
	v_mov_b32_e32 v76, v2
	v_mov_b32_e32 v77, v2
	v_mov_b32_e32 v78, v2
	v_mov_b32_e32 v79, v2
	v_mov_b32_e32 v80, v2
	v_mov_b32_e32 v81, v2
	v_mov_b32_e32 v90, v2
	v_mov_b32_e32 v91, v2
	v_mov_b32_e32 v92, v2
	v_mov_b32_e32 v93, v2
	v_mov_b32_e32 v94, v2
	v_mov_b32_e32 v95, v2
	v_mov_b32_e32 v96, v2
	v_mov_b32_e32 v97, v2
	v_mov_b32_e32 v106, v2
	v_mov_b32_e32 v107, v2
	v_mov_b32_e32 v108, v2
	v_mov_b32_e32 v109, v2
	v_mov_b32_e32 v110, v2
	v_mov_b32_e32 v111, v2
	v_mov_b32_e32 v112, v2
	v_mov_b32_e32 v113, v2
	v_mov_b32_e32 v82, v2
	v_mov_b32_e32 v83, v2
	v_mov_b32_e32 v84, v2
	v_mov_b32_e32 v85, v2
	v_mov_b32_e32 v86, v2
	v_mov_b32_e32 v87, v2
	v_mov_b32_e32 v88, v2
	v_mov_b32_e32 v89, v2
	v_mov_b32_e32 v98, v2
	v_mov_b32_e32 v99, v2
	v_mov_b32_e32 v100, v2
	v_mov_b32_e32 v101, v2
	v_mov_b32_e32 v102, v2
	v_mov_b32_e32 v103, v2
	v_mov_b32_e32 v104, v2
	v_mov_b32_e32 v105, v2
	v_mov_b32_e32 v114, v2
	v_mov_b32_e32 v115, v2
	v_mov_b32_e32 v116, v2
	v_mov_b32_e32 v117, v2
	v_mov_b32_e32 v118, v2
	v_mov_b32_e32 v119, v2
	v_mov_b32_e32 v120, v2
	v_mov_b32_e32 v121, v2
	v_mov_b32_e32 v122, v2
	v_mov_b32_e32 v123, v2
	v_mov_b32_e32 v124, v2
	v_mov_b32_e32 v125, v2
	v_mov_b32_e32 v126, v2
	v_mov_b32_e32 v127, v2
	v_mov_b32_e32 v128, v2
	v_mov_b32_e32 v129, v2

; #define LAS __attribute__((address_space(3)))
; __device__ __forceinline__ float bflo(unsigned w) { return __uint_as_float(w << 16); }
; __device__ __forceinline__ float bfhi(unsigned w) { return __uint_as_float(w & 0xffff0000u); }
; __device__ __forceinline__ unsigned pk2(float lo, float hi) { unsigned r; asm("v_cvt_pk_bf16_f32 %0, %1, %2" : "=v"(r) : "v"(lo), "v"(hi)); return r; }
; __device__ __forceinline__ void phase_attn(const Params& p, int l, LAS unsigned char* lds, int bid, int G, int tid) {
;     ...
;         for (int blk = 0; blk < 2; ++blk) {
;             const int tq = t0 + R * 64 + qh * 32 + blk * 16 + fr;
;             float qv[4][8]; float ss = 0.f;
; #pragma unroll
;             for (int ks = 0; ks < 4; ++ks) { const u32x4 raw = *(const u32x4*)(proja + (size_t)tq * PA_LD + h * 128 + ks * 32 + g * 8);
;                 qv[ks][0] = bflo(raw.x); qv[ks][1] = bfhi(raw.x); qv[ks][2] = bflo(raw.y); qv[ks][3] = bfhi(raw.y); qv[ks][4] = bflo(raw.z); qv[ks][5] = bfhi(raw.z); qv[ks][6] = bflo(raw.w); qv[ks][7] = bfhi(raw.w);
; #pragma unroll
;                 for (int j = 0; j < 8; ++j) ss += qv[ks][j] * qv[ks][j]; }
;             ss += __shfl_xor(ss, 16); ss += __shfl_xor(ss, 32);
;             const float rs = rsqrtf(ss * (1.f / 128.f) + 1e-6f);
; #pragma unroll
;             for (int ks = 0; ks < 4; ++ks) { unsigned w[4]; const f32x4 ga = *(const LAS f32x4*)(gqk + ks * 32 + g * 8), gb = *(const LAS f32x4*)(gqk + ks * 32 + g * 8 + 4);
; #pragma unroll
;                 for (int j = 0; j < 4; ++j) { const float m0 = j < 2 ? ga[2 * j] : gb[2 * j - 4], m1 = j < 2 ? ga[2 * j + 1] : gb[2 * j - 3]; w[j] = pk2(qv[ks][2 * j] * rs * m0, qv[ks][2 * j + 1] * rs * m1); }
;                 u32x4 v; v.x = w[0]; v.y = w[1]; v.z = w[2]; v.w = w[3]; Qf[blk][ks] = __builtin_bit_cast(bf16x8, v); }
.LBB0_202:
	s_lshl_b32 s3, s3, 2
	s_and_b32 s3, s4, s3
	s_and_b32 s94, s42, 7
	v_add_u32_e32 v116, s3, v162
	v_sub_u32_e64 v2, s3, 1 clamp
	v_sub_u32_e64 v1, s3, 4 clamp
	v_readfirstlane_b32 s3, v2
	v_lshlrev_b32_e32 v2, 6, v116
	s_lshl_b32 s14, s94, 8
	v_add3_u32 v136, s22, v143, v2
	v_lshl_add_u64 v[2:3], v[124:125], 0, s[14:15]
	s_movk_i32 s14, 0x1400
	v_mad_i64_i32 v[4:5], s[4:5], v136, s14, v[2:3]
	global_load_dwordx4 v[6:9], v[4:5], off
	global_load_dwordx4 v[236:239], v[4:5], off offset:64
	global_load_dwordx4 v[240:243], v[4:5], off offset:128
	global_load_dwordx4 v[244:247], v[4:5], off offset:192
	v_add_u32_e32 v138, 16, v136
	v_mad_i64_i32 v[2:3], s[4:5], v138, s14, v[2:3]
	s_min_u32 s3, s3, s40
	v_readfirstlane_b32 s4, v1
	s_add_i32 s41, s3, 7
	s_min_u32 s18, s4, s40
	s_lshl_b32 s43, s94, 7
	s_sub_i32 s19, s41, s18
	s_cmp_lt_i32 s19, 0
	s_waitcnt vmcnt(3)
	v_lshlrev_b32_e32 v10, 16, v6
	v_and_b32_e32 v11, 0xffff0000, v6
	v_lshlrev_b32_e32 v12, 16, v7
	v_and_b32_e32 v13, 0xffff0000, v7
	v_lshlrev_b32_e32 v14, 16, v8
	v_and_b32_e32 v15, 0xffff0000, v8
	v_lshlrev_b32_e32 v30, 16, v9
	v_and_b32_e32 v31, 0xffff0000, v9
	v_mul_f32_e32 v18, v11, v11
	v_fmac_f32_e32 v18, v10, v10
	v_fmac_f32_e32 v18, v12, v12
	v_fmac_f32_e32 v18, v13, v13
	v_fmac_f32_e32 v18, v14, v14
	v_fmac_f32_e32 v18, v15, v15
	v_fmac_f32_e32 v18, v30, v30
	v_fmac_f32_e32 v18, v31, v31
	s_waitcnt vmcnt(2)
	v_lshlrev_b32_e32 v34, 16, v236
	v_and_b32_e32 v35, 0xffff0000, v236
	v_lshlrev_b32_e32 v36, 16, v237
	v_and_b32_e32 v37, 0xffff0000, v237
	v_lshlrev_b32_e32 v38, 16, v238
	v_and_b32_e32 v39, 0xffff0000, v238
	v_lshlrev_b32_e32 v40, 16, v239
	v_and_b32_e32 v41, 0xffff0000, v239
	v_fmac_f32_e32 v18, v34, v34
	v_fmac_f32_e32 v18, v35, v35
	v_fmac_f32_e32 v18, v36, v36
	v_fmac_f32_e32 v18, v37, v37
	v_fmac_f32_e32 v18, v38, v38
	v_fmac_f32_e32 v18, v39, v39
	v_fmac_f32_e32 v18, v40, v40
	v_fmac_f32_e32 v18, v41, v41
	s_waitcnt vmcnt(1)
	v_lshlrev_b32_e32 v50, 16, v240
	v_and_b32_e32 v51, 0xffff0000, v240
	v_lshlrev_b32_e32 v52, 16, v241
	v_and_b32_e32 v53, 0xffff0000, v241
	v_fmac_f32_e32 v18, v50, v50
	v_fmac_f32_e32 v18, v51, v51
	v_fmac_f32_e32 v18, v52, v52
	v_lshlrev_b32_e32 v56, 16, v242
	v_fmac_f32_e32 v18, v53, v53
	v_and_b32_e32 v57, 0xffff0000, v242
	v_fmac_f32_e32 v18, v56, v56
	v_lshlrev_b32_e32 v58, 16, v243
	v_fmac_f32_e32 v18, v57, v57
	v_and_b32_e32 v59, 0xffff0000, v243
	v_fmac_f32_e32 v18, v58, v58
	v_fmac_f32_e32 v18, v59, v59
	ds_read_b128 v[26:29], v165 offset:38400
	ds_read_b128 v[22:25], v165 offset:38416
	s_waitcnt vmcnt(0)
	v_and_b32_e32 v16, 0xffff0000, v244
	v_lshlrev_b32_e32 v17, 16, v244
	v_pk_mul_f32 v[8:9], v[16:17], v[16:17]
	v_and_b32_e32 v54, 0xffff0000, v245
	v_add_f32_e32 v4, v9, v18
	v_lshlrev_b32_e32 v55, 16, v245
	v_add_f32_e32 v8, v8, v4
	v_pk_mul_f32 v[4:5], v[54:55], v[54:55]
	v_and_b32_e32 v18, 0xffff0000, v246
	v_add_f32_e32 v5, v5, v8
	v_lshlrev_b32_e32 v19, 16, v246
	v_add_f32_e32 v8, v4, v5
	v_pk_mul_f32 v[4:5], v[18:19], v[18:19]
	v_and_b32_e32 v20, 0xffff0000, v247
	v_add_f32_e32 v5, v5, v8
	v_lshlrev_b32_e32 v21, 16, v247
	v_add_f32_e32 v6, v4, v5
	v_pk_mul_f32 v[4:5], v[20:21], v[20:21]
	s_nop 0
	v_add_f32_e32 v5, v5, v6
	v_add_f32_e32 v4, v4, v5
	ds_bpermute_b32 v5, v169, v4
	s_waitcnt lgkmcnt(0)
	v_add_f32_e32 v4, v4, v5
	ds_bpermute_b32 v5, v170, v4
	s_waitcnt lgkmcnt(0)
	v_add_f32_e32 v4, v4, v5
	v_fmamk_f32 v4, v4, 0x3c000000, v178
	v_cmp_gt_f32_e32 vcc, s55, v4
	v_mul_f32_e32 v5, 0x4b800000, v4
	s_nop 0
	v_cndmask_b32_e32 v4, v4, v5, vcc
	v_rsq_f32_e32 v4, v4
	s_nop 0
	v_mul_f32_e32 v5, 0x45800000, v4
	v_cndmask_b32_e32 v60, v4, v5, vcc
	v_mul_f32_e32 v4, v60, v10
	v_mul_f32_e32 v5, v60, v11
	v_mul_f32_e32 v4, v26, v4
	v_mul_f32_e32 v5, v27, v5
	v_cvt_pk_bf16_f32 v4, v4, v5
	v_mul_f32_e32 v5, v60, v12
	v_mul_f32_e32 v6, v60, v13
	v_mul_f32_e32 v5, v28, v5
	v_mul_f32_e32 v6, v29, v6
	v_cvt_pk_bf16_f32 v5, v5, v6
	v_mul_f32_e32 v6, v60, v14
	v_mul_f32_e32 v7, v60, v15
	v_mul_f32_e32 v6, v22, v6
	v_mul_f32_e32 v7, v23, v7
	v_cvt_pk_bf16_f32 v6, v6, v7
	v_mul_f32_e32 v7, v60, v30
	v_mul_f32_e32 v8, v60, v31
	ds_read_b128 v[42:45], v165 offset:38528
	ds_read_b128 v[30:33], v165 offset:38544
	v_mul_f32_e32 v7, v24, v7
	v_mul_f32_e32 v8, v25, v8
	v_cvt_pk_bf16_f32 v7, v7, v8
	v_mul_f32_e32 v8, v60, v34
	v_mul_f32_e32 v9, v60, v35
	s_waitcnt lgkmcnt(1)
	v_mul_f32_e32 v8, v42, v8
	v_mul_f32_e32 v9, v43, v9
	v_cvt_pk_bf16_f32 v8, v8, v9
	v_mul_f32_e32 v9, v60, v36
	v_mul_f32_e32 v10, v60, v37
	v_mul_f32_e32 v9, v44, v9
	v_mul_f32_e32 v10, v45, v10
	v_cvt_pk_bf16_f32 v9, v9, v10
	v_mul_f32_e32 v10, v60, v38
	v_mul_f32_e32 v11, v60, v39
	s_waitcnt lgkmcnt(0)
	v_mul_f32_e32 v10, v30, v10
	v_mul_f32_e32 v11, v31, v11
	ds_read_b128 v[46:49], v165 offset:38656
	ds_read_b128 v[34:37], v165 offset:38672
	v_cvt_pk_bf16_f32 v10, v10, v11
	v_mul_f32_e32 v11, v60, v40
	v_mul_f32_e32 v12, v60, v41
	v_mul_f32_e32 v11, v32, v11
	v_mul_f32_e32 v12, v33, v12
	v_cvt_pk_bf16_f32 v11, v11, v12
	v_mul_f32_e32 v12, v60, v50
	v_mul_f32_e32 v13, v60, v51
	s_waitcnt lgkmcnt(1)
	v_mul_f32_e32 v12, v46, v12
	v_mul_f32_e32 v13, v47, v13
	v_cvt_pk_bf16_f32 v12, v12, v13
	v_mul_f32_e32 v13, v60, v52
	v_mul_f32_e32 v14, v60, v53
	v_mul_f32_e32 v13, v48, v13
	v_mul_f32_e32 v14, v49, v14
	v_cvt_pk_bf16_f32 v13, v13, v14
	v_mul_f32_e32 v14, v60, v56
	v_mul_f32_e32 v15, v60, v57
	s_waitcnt lgkmcnt(0)
	v_mul_f32_e32 v14, v34, v14
	v_mul_f32_e32 v15, v35, v15
	v_cvt_pk_bf16_f32 v14, v14, v15
	v_mul_f32_e32 v15, v60, v58
	v_mul_f32_e32 v38, v60, v59
	v_mul_f32_e32 v15, v36, v15
	v_mul_f32_e32 v38, v37, v38
	v_cvt_pk_bf16_f32 v15, v15, v38
	ds_read_b128 v[50:53], v165 offset:38784
	ds_read_b128 v[38:41], v165 offset:38800
	v_mul_f32_e32 v17, v60, v17
	v_mul_f32_e32 v16, v60, v16
	v_mul_f32_e32 v54, v60, v54
	s_waitcnt lgkmcnt(1)
; #define LAS __attribute__((address_space(3)))
; __device__ __forceinline__ float bflo(unsigned w) { return __uint_as_float(w << 16); }
; __device__ __forceinline__ float bfhi(unsigned w) { return __uint_as_float(w & 0xffff0000u); }
; __device__ __forceinline__ unsigned pk2(float lo, float hi) { unsigned r; asm("v_cvt_pk_bf16_f32 %0, %1, %2" : "=v"(r) : "v"(lo), "v"(hi)); return r; }
; __device__ __forceinline__ void phase_attn(const Params& p, int l, LAS unsigned char* lds, int bid, int G, int tid) {
;     ...
;         for (int blk = 0; blk < 2; ++blk) {
;             const int tq = t0 + R * 64 + qh * 32 + blk * 16 + fr;
;             float qv[4][8]; float ss = 0.f;
; #pragma unroll
;             for (int ks = 0; ks < 4; ++ks) { const u32x4 raw = *(const u32x4*)(proja + (size_t)tq * PA_LD + h * 128 + ks * 32 + g * 8);
;                 qv[ks][0] = bflo(raw.x); qv[ks][1] = bfhi(raw.x); qv[ks][2] = bflo(raw.y); qv[ks][3] = bfhi(raw.y); qv[ks][4] = bflo(raw.z); qv[ks][5] = bfhi(raw.z); qv[ks][6] = bflo(raw.w); qv[ks][7] = bfhi(raw.w);
; #pragma unroll
;                 for (int j = 0; j < 8; ++j) ss += qv[ks][j] * qv[ks][j]; }
;             ss += __shfl_xor(ss, 16); ss += __shfl_xor(ss, 32);
;             const float rs = rsqrtf(ss * (1.f / 128.f) + 1e-6f);
; #pragma unroll
;             for (int ks = 0; ks < 4; ++ks) { unsigned w[4]; const f32x4 ga = *(const LAS f32x4*)(gqk + ks * 32 + g * 8), gb = *(const LAS f32x4*)(gqk + ks * 32 + g * 8 + 4);
; #pragma unroll
;                 for (int j = 0; j < 4; ++j) { const float m0 = j < 2 ? ga[2 * j] : gb[2 * j - 4], m1 = j < 2 ? ga[2 * j + 1] : gb[2 * j - 3]; w[j] = pk2(qv[ks][2 * j] * rs * m0, qv[ks][2 * j + 1] * rs * m1); }
;                 u32x4 v; v.x = w[0]; v.y = w[1]; v.z = w[2]; v.w = w[3]; Qf[blk][ks] = __builtin_bit_cast(bf16x8, v); }
	v_mul_f32_e32 v17, v50, v17
	v_mul_f32_e32 v16, v51, v16
	v_cvt_pk_bf16_f32 v16, v17, v16
	v_mul_f32_e32 v17, v60, v55
	v_mul_f32_e32 v17, v52, v17
	v_mul_f32_e32 v54, v53, v54
	v_cvt_pk_bf16_f32 v17, v17, v54
	global_load_dwordx4 v[54:57], v[2:3], off
	global_load_dwordx4 v[236:239], v[2:3], off offset:64
	global_load_dwordx4 v[240:243], v[2:3], off offset:128
	global_load_dwordx4 v[244:247], v[2:3], off offset:192
	v_mul_f32_e32 v19, v60, v19
	v_mul_f32_e32 v18, v60, v18
	s_waitcnt lgkmcnt(0)
	v_mul_f32_e32 v19, v38, v19
	v_mul_f32_e32 v18, v39, v18
	v_cvt_pk_bf16_f32 v18, v19, v18
	v_mul_f32_e32 v19, v60, v21
	v_mul_f32_e32 v20, v60, v20
	v_mul_f32_e32 v19, v40, v19
	v_mul_f32_e32 v20, v41, v20
	v_cvt_pk_bf16_f32 v19, v19, v20
	s_waitcnt vmcnt(3)
	v_lshlrev_b32_e32 v63, 16, v54
	v_and_b32_e32 v20, 0xffff0000, v54
	v_lshlrev_b32_e32 v62, 16, v55
	v_and_b32_e32 v21, 0xffff0000, v55
	v_lshlrev_b32_e32 v61, 16, v56
	v_and_b32_e32 v60, 0xffff0000, v56
	v_lshlrev_b32_e32 v59, 16, v57
	v_and_b32_e32 v58, 0xffff0000, v57
	v_mul_f32_e32 v68, v20, v20
	v_fmac_f32_e32 v68, v63, v63
	v_fmac_f32_e32 v68, v62, v62
	v_fmac_f32_e32 v68, v21, v21
	v_fmac_f32_e32 v68, v61, v61
	v_fmac_f32_e32 v68, v60, v60
	v_fmac_f32_e32 v68, v59, v59
	v_fmac_f32_e32 v68, v58, v58
	s_waitcnt vmcnt(2)
	v_lshlrev_b32_e32 v72, 16, v236
	v_and_b32_e32 v71, 0xffff0000, v236
	v_lshlrev_b32_e32 v70, 16, v237
	v_and_b32_e32 v69, 0xffff0000, v237
	v_lshlrev_b32_e32 v67, 16, v238
	v_and_b32_e32 v66, 0xffff0000, v238
	v_lshlrev_b32_e32 v65, 16, v239
	v_and_b32_e32 v64, 0xffff0000, v239
	v_fmac_f32_e32 v68, v72, v72
	v_fmac_f32_e32 v68, v71, v71
	v_fmac_f32_e32 v68, v70, v70
	v_fmac_f32_e32 v68, v69, v69
	v_fmac_f32_e32 v68, v67, v67
	v_fmac_f32_e32 v68, v66, v66
	v_fmac_f32_e32 v68, v65, v65
	v_fmac_f32_e32 v68, v64, v64
	s_waitcnt vmcnt(1)
	v_lshlrev_b32_e32 v80, 16, v240
	v_and_b32_e32 v79, 0xffff0000, v240
	v_lshlrev_b32_e32 v78, 16, v241
	v_and_b32_e32 v77, 0xffff0000, v241
	v_lshlrev_b32_e32 v76, 16, v242
	v_and_b32_e32 v75, 0xffff0000, v242
	v_lshlrev_b32_e32 v74, 16, v243
	v_and_b32_e32 v73, 0xffff0000, v243
	v_fmac_f32_e32 v68, v80, v80
	v_fmac_f32_e32 v68, v79, v79
	v_fmac_f32_e32 v68, v78, v78
	v_fmac_f32_e32 v68, v77, v77
	v_fmac_f32_e32 v68, v76, v76
	v_fmac_f32_e32 v68, v75, v75
	v_fmac_f32_e32 v68, v74, v74
	v_fmac_f32_e32 v68, v73, v73
	s_waitcnt vmcnt(0)
	v_and_b32_e32 v2, 0xffff0000, v244
	v_lshlrev_b32_e32 v3, 16, v244
	v_pk_mul_f32 v[82:83], v[2:3], v[2:3]
	s_nop 0
	v_add_f32_e32 v54, v83, v68
	v_add_f32_e32 v68, v82, v54
	v_and_b32_e32 v54, 0xffff0000, v245
	v_lshlrev_b32_e32 v55, 16, v245
	v_pk_mul_f32 v[82:83], v[54:55], v[54:55]
	s_nop 0
	v_add_f32_e32 v68, v83, v68
	v_add_f32_e32 v68, v82, v68
	v_and_b32_e32 v82, 0xffff0000, v246
	v_lshlrev_b32_e32 v83, 16, v246
	v_pk_mul_f32 v[84:85], v[82:83], v[82:83]
	s_nop 0
	v_add_f32_e32 v56, v85, v68
	v_add_f32_e32 v68, v84, v56
	v_and_b32_e32 v56, 0xffff0000, v247
	v_lshlrev_b32_e32 v57, 16, v247
	v_pk_mul_f32 v[84:85], v[56:57], v[56:57]
	s_nop 0
	v_add_f32_e32 v68, v85, v68
	v_add_f32_e32 v68, v84, v68
	ds_bpermute_b32 v81, v169, v68
	s_waitcnt lgkmcnt(0)
	v_add_f32_e32 v68, v68, v81
	ds_bpermute_b32 v81, v170, v68
	s_waitcnt lgkmcnt(0)
	v_add_f32_e32 v68, v68, v81
	v_fmamk_f32 v68, v68, 0x3c000000, v178
	v_cmp_gt_f32_e32 vcc, s55, v68
	v_mul_f32_e32 v81, 0x4b800000, v68
	s_nop 0
	v_cndmask_b32_e32 v68, v68, v81, vcc
	v_rsq_f32_e32 v68, v68
	s_nop 0
	v_mul_f32_e32 v81, 0x45800000, v68
	v_cndmask_b32_e32 v68, v68, v81, vcc
	v_mul_f32_e32 v63, v68, v63
	v_mul_f32_e32 v20, v68, v20
	v_mul_f32_e32 v26, v26, v63
	v_mul_f32_e32 v20, v27, v20
	v_cvt_pk_bf16_f32 v20, v26, v20
	v_mul_f32_e32 v26, v68, v62
	v_mul_f32_e32 v21, v68, v21
	v_mul_f32_e32 v26, v28, v26
	v_mul_f32_e32 v21, v29, v21
	v_cvt_pk_bf16_f32 v21, v26, v21
	v_mul_f32_e32 v26, v68, v61
	v_mul_f32_e32 v22, v22, v26
	v_mul_f32_e32 v26, v68, v60
	v_mul_f32_e32 v23, v23, v26
	v_cvt_pk_bf16_f32 v22, v22, v23
	v_mul_f32_e32 v23, v68, v59
	v_mul_f32_e32 v23, v24, v23
	v_mul_f32_e32 v24, v68, v58
	v_mul_f32_e32 v24, v25, v24
	v_cvt_pk_bf16_f32 v23, v23, v24
	v_mul_f32_e32 v24, v68, v72
	v_mul_f32_e32 v25, v68, v71
	v_mul_f32_e32 v24, v42, v24
	v_mul_f32_e32 v25, v43, v25
	v_cvt_pk_bf16_f32 v24, v24, v25
	v_mul_f32_e32 v25, v68, v70
	v_mul_f32_e32 v26, v68, v69
	v_mul_f32_e32 v25, v44, v25
	v_mul_f32_e32 v26, v45, v26
	v_cvt_pk_bf16_f32 v25, v25, v26
	v_mul_f32_e32 v26, v68, v67
	v_mul_f32_e32 v27, v68, v66
	v_mul_f32_e32 v26, v30, v26
	v_mul_f32_e32 v27, v31, v27
	v_cvt_pk_bf16_f32 v26, v26, v27
	v_mul_f32_e32 v27, v68, v65
	v_mul_f32_e32 v28, v68, v64
	v_mul_f32_e32 v27, v32, v27
	v_mul_f32_e32 v28, v33, v28
	v_cvt_pk_bf16_f32 v27, v27, v28
	v_mul_f32_e32 v28, v68, v80
	v_mul_f32_e32 v29, v68, v79
	v_mul_f32_e32 v28, v46, v28
	v_mul_f32_e32 v29, v47, v29
	v_cvt_pk_bf16_f32 v28, v28, v29
	v_mul_f32_e32 v29, v68, v78
	v_mul_f32_e32 v30, v68, v77
	v_mul_f32_e32 v29, v48, v29
	v_mul_f32_e32 v30, v49, v30
	v_cvt_pk_bf16_f32 v29, v29, v30
	v_mul_f32_e32 v30, v68, v76
	v_mul_f32_e32 v31, v68, v75
	v_mul_f32_e32 v30, v34, v30
	v_mul_f32_e32 v31, v35, v31
	v_cvt_pk_bf16_f32 v30, v30, v31
	v_mul_f32_e32 v31, v68, v74
	v_mul_f32_e32 v32, v68, v73
	v_mul_f32_e32 v3, v68, v3
	v_mul_f32_e32 v2, v68, v2
	v_mul_f32_e32 v31, v36, v31
	v_mul_f32_e32 v32, v37, v32
	v_mul_f32_e32 v3, v50, v3
	v_mul_f32_e32 v2, v51, v2
	v_cvt_pk_bf16_f32 v31, v31, v32
	v_cvt_pk_bf16_f32 v32, v3, v2
	v_mul_f32_e32 v2, v68, v55
	v_mul_f32_e32 v3, v68, v54
	v_mul_f32_e32 v2, v52, v2
	v_mul_f32_e32 v3, v53, v3
	v_cvt_pk_bf16_f32 v33, v2, v3
	v_mul_f32_e32 v2, v68, v83
	v_mul_f32_e32 v3, v68, v82
	v_mul_f32_e32 v2, v38, v2
	v_mul_f32_e32 v3, v39, v3
	v_cvt_pk_bf16_f32 v34, v2, v3
	v_mul_f32_e32 v2, v68, v57
	v_mul_f32_e32 v3, v68, v56
	v_mul_f32_e32 v2, v40, v2
	v_mul_f32_e32 v3, v41, v3
	v_cvt_pk_bf16_f32 v35, v2, v3
	s_cbranch_scc1 .LBB0_195
; __device__ __forceinline__ void phase_attn(const Params& p, int l, LAS unsigned char* lds, int bid, int G, int tid) {
;     ...
;         { const int tk0 = t0 + kmin * 64;
; #pragma unroll
;             for (int e = 0; e < 2; ++e) { kraw[e] = *(const u32x4*)(proja + (size_t)(tk0 + skey) * PA_LD + 1024 + h * 128 + spart * 16 + e * 8);
;                 vraw[e] = *(const u32x4*)(tt + (size_t)(h * 128 + sd) * T + tk0 + sq * 16 + e * 8); } }
;         for (int kk = 0; kk < nk; ++kk) {
;             const int KR = kmin + kk;
;             __syncthreads();
;             {
;                 if (kk == 0) { if (tid < 465) rl[tid] = rpb[h * 465 + tid]; }
	s_lshl_b32 s4, s18, 6
	s_add_i32 s22, s4, s22
	v_readlane_b32 s4, v253, 7
	v_readlane_b32 s5, v253, 8
	v_add_u32_e32 v36, s22, v163
	s_ashr_i32 s23, s22, 31
	v_mov_b64_e32 v[2:3], s[4:5]
	v_mad_i64_i32 v[2:3], s[4:5], v36, s14, v[2:3]
	s_lshl_b32 s14, s43, 1
	v_lshl_add_u64 v[36:37], v[2:3], 0, s[14:15]
	v_lshlrev_b32_e32 v2, 1, v126
	v_mov_b32_e32 v3, v0
	v_lshl_add_u64 v[40:41], v[36:37], 0, v[2:3]
	v_add_u32_e32 v36, s43, v164
	v_ashrrev_i32_e32 v37, 31, v36
	v_lshlrev_b64 v[52:53], 16, v[36:37]
	v_lshl_add_u64 v[36:37], s[92:93], 0, v[52:53]
	v_lshl_add_u64 v[36:37], s[22:23], 1, v[36:37]
	v_mov_b32_e32 v135, v0
	v_lshl_add_u64 v[48:49], v[36:37], 0, v[134:135]
	global_load_dwordx4 v[36:39], v[40:41], off offset:2064
	s_nop 0
	global_load_dwordx4 v[40:43], v[40:41], off offset:2048
	s_nop 0
	global_load_dwordx4 v[44:47], v[48:49], off offset:16
	s_nop 0
	global_load_dwordx4 v[48:51], v[48:49], off
	s_movk_i32 s45, 0x1400
	s_barrier
	s_and_saveexec_b64 s[4:5], s[0:1]
	s_cbranch_execz .LBB0_205
	s_mulk_i32 s94, 0x1d1
	v_add_u32_e32 v54, s94, v194
	v_ashrrev_i32_e32 v55, 31, v54
	v_lshl_add_u64 v[54:55], v[54:55], 2, s[6:7]
	global_load_dword v3, v[54:55], off
	s_waitcnt vmcnt(0)
	ds_write_b32 v127, v3 offset:35840

; #define PG8_STAGE(bufoff, gbase, voff) do { _Pragma("unroll") for (int _i = 0; _i < 2; ++_i) \
;         __builtin_amdgcn_global_load_lds((const unsigned*)((const char*)(gbase) + (voff)[_i]), (LAS unsigned*)(lds + (bufoff) + ldsw + _i * 8192), 16, 0, 0); } while (0)
; #define PG8_LDA(dst, b, h) do { _Pragma("unroll") for (int m = 0; m < 4; ++m) _Pragma("unroll") for (int k = 0; k < 2; ++k) dst[m][k] = *(const LAS bf16x8*)(lds + PG8_SA(b, h) + aoff + m * 2048 + k * 1024); } while (0)
; #define PG8_LDB(dst, b, h) do { _Pragma("unroll") for (int n = 0; n < 2; ++n) _Pragma("unroll") for (int k = 0; k < 2; ++k) dst[n][k] = *(const LAS bf16x8*)(lds + PG8_SB(b, h) + boff + n * 2048 + k * 1024); } while (0)
; #define PG8_SCHED __builtin_amdgcn_sched_barrier(0)
; template <class Epi, class Sched>
; __device__ __forceinline__ void gemm_phase(LAS unsigned char* lds, const int tid, const int K, const int ldaB, const int ldbB, const Sched& S, const Epi& E) {
;     ...
;         const char* nA = has_next ? nxt.A : cA; const char* nB = has_next ? nxt.B : cB;
;         for (int t = 0; t < nt; t += 2) {
;             const bool last = (t == nt - 2);
;             const char* a1 = cA + (size_t)(t + 1) * kstep;
;             const char* a2 = last ? nA : cA + (size_t)(t + 2) * kstep; const char* b2 = last ? nB : cB + (size_t)(t + 2) * kstep;
;             const char* a3 = a2 + kstep; const char* b3 = b2 + kstep;
;             PG8_LDB(B0, 0, 0); PG8_LDB(B1, 0, 1); PG8_SCHED; PG8_LDA(At, 0, 0); PG8_STAGE(PG8_SA(1, 1), a1 + hstepA, voffA);
;     ...
;         for (int a = 0; a < 2; ++a)
; #pragma unroll
;             for (int b = 0; b < 2; ++b)
; #pragma unroll
;                 for (int m = 0; m < 4; ++m)
; #pragma unroll
;                     for (int n = 0; n < 2; ++n) acc[a][b][m][n] = (f32x4){0.f, 0.f, 0.f, 0.f};
.LBB0_354:
	s_add_u32 s42, s12, 0x100
	s_addc_u32 s43, s13, 0
	s_add_u32 s12, s22, 0x160080
	v_mov_b32_e32 v2, 0
	s_addc_u32 s13, s23, 0
	s_mov_b32 s48, -2
	v_mov_b32_e32 v3, v2
	v_mov_b32_e32 v4, v2
	v_mov_b32_e32 v5, v2
	v_mov_b32_e32 v6, v2
	v_mov_b32_e32 v7, v2
	v_mov_b32_e32 v8, v2
	v_mov_b32_e32 v9, v2
	v_mov_b32_e32 v18, v2
	v_mov_b32_e32 v19, v2
	v_mov_b32_e32 v20, v2
	v_mov_b32_e32 v21, v2
	v_mov_b32_e32 v22, v2
	v_mov_b32_e32 v23, v2
	v_mov_b32_e32 v24, v2
	v_mov_b32_e32 v25, v2
	v_mov_b32_e32 v34, v2
	v_mov_b32_e32 v35, v2
	v_mov_b32_e32 v36, v2
	v_mov_b32_e32 v37, v2
	v_mov_b32_e32 v38, v2
	v_mov_b32_e32 v39, v2
	v_mov_b32_e32 v40, v2
	v_mov_b32_e32 v41, v2
	v_mov_b32_e32 v66, v2
	v_mov_b32_e32 v67, v2
	v_mov_b32_e32 v68, v2
	v_mov_b32_e32 v69, v2
	v_mov_b32_e32 v70, v2
	v_mov_b32_e32 v71, v2
	v_mov_b32_e32 v72, v2
	v_mov_b32_e32 v73, v2
	v_mov_b32_e32 v10, v2
	v_mov_b32_e32 v11, v2
	v_mov_b32_e32 v12, v2
	v_mov_b32_e32 v13, v2
	v_mov_b32_e32 v14, v2
	v_mov_b32_e32 v15, v2
	v_mov_b32_e32 v16, v2
	v_mov_b32_e32 v17, v2
	v_mov_b32_e32 v26, v2
	v_mov_b32_e32 v27, v2
	v_mov_b32_e32 v28, v2
	v_mov_b32_e32 v29, v2
	v_mov_b32_e32 v30, v2
	v_mov_b32_e32 v31, v2
	v_mov_b32_e32 v32, v2
	v_mov_b32_e32 v33, v2
	v_mov_b32_e32 v42, v2
	v_mov_b32_e32 v43, v2
	v_mov_b32_e32 v44, v2
	v_mov_b32_e32 v45, v2
	v_mov_b32_e32 v46, v2
	v_mov_b32_e32 v47, v2
	v_mov_b32_e32 v48, v2
	v_mov_b32_e32 v49, v2
	v_mov_b32_e32 v74, v2
	v_mov_b32_e32 v75, v2
	v_mov_b32_e32 v76, v2
	v_mov_b32_e32 v77, v2
	v_mov_b32_e32 v78, v2
	v_mov_b32_e32 v79, v2
	v_mov_b32_e32 v80, v2
	v_mov_b32_e32 v81, v2
	v_mov_b32_e32 v82, v2
	v_mov_b32_e32 v83, v2
	v_mov_b32_e32 v84, v2
	v_mov_b32_e32 v85, v2
	v_mov_b32_e32 v86, v2
	v_mov_b32_e32 v87, v2
	v_mov_b32_e32 v88, v2
	v_mov_b32_e32 v89, v2
	v_mov_b32_e32 v98, v2
	v_mov_b32_e32 v99, v2
	v_mov_b32_e32 v100, v2
	v_mov_b32_e32 v101, v2
	v_mov_b32_e32 v102, v2
	v_mov_b32_e32 v103, v2
	v_mov_b32_e32 v104, v2
	v_mov_b32_e32 v105, v2
	v_mov_b32_e32 v106, v2
	v_mov_b32_e32 v107, v2
	v_mov_b32_e32 v108, v2
	v_mov_b32_e32 v109, v2
	v_mov_b32_e32 v110, v2
	v_mov_b32_e32 v111, v2
	v_mov_b32_e32 v112, v2
	v_mov_b32_e32 v113, v2
	v_mov_b32_e32 v130, v2
	v_mov_b32_e32 v131, v2
	v_mov_b32_e32 v132, v2
	v_mov_b32_e32 v133, v2
	v_mov_b32_e32 v134, v2
	v_mov_b32_e32 v135, v2
	v_mov_b32_e32 v136, v2
	v_mov_b32_e32 v137, v2
	v_mov_b32_e32 v90, v2
	v_mov_b32_e32 v91, v2
	v_mov_b32_e32 v92, v2
	v_mov_b32_e32 v93, v2
	v_mov_b32_e32 v94, v2
	v_mov_b32_e32 v95, v2
	v_mov_b32_e32 v96, v2
	v_mov_b32_e32 v97, v2
	v_mov_b32_e32 v114, v2
	v_mov_b32_e32 v115, v2
	v_mov_b32_e32 v116, v2
	v_mov_b32_e32 v117, v2
	v_mov_b32_e32 v118, v2
	v_mov_b32_e32 v119, v2
	v_mov_b32_e32 v120, v2
	v_mov_b32_e32 v121, v2
	v_mov_b32_e32 v122, v2
	v_mov_b32_e32 v123, v2
	v_mov_b32_e32 v124, v2
	v_mov_b32_e32 v125, v2
	v_mov_b32_e32 v126, v2
	v_mov_b32_e32 v127, v2
	v_mov_b32_e32 v128, v2
	v_mov_b32_e32 v129, v2
	v_mov_b32_e32 v138, v2
	v_mov_b32_e32 v139, v2
	v_mov_b32_e32 v140, v2
	v_mov_b32_e32 v141, v2
	v_mov_b32_e32 v142, v2
	v_mov_b32_e32 v143, v2
	v_mov_b32_e32 v144, v2
	v_mov_b32_e32 v145, v2
